# cmp_w1^T bf16 copy stored in MFMA-fragment order (coalesced 1 KiB fragment loads in the compression MLP), deeper load pipeline there
# speedup vs baseline: 1.0214x; 1.0034x over previous
.LBB0_124:
	s_andn2_b64 vcc, exec, s[2:3]
	s_cbranch_vccnz .LBB0_115
	s_mov_b64 s[2:3], s[44:45]
	s_load_dwordx2 s[2:3], s[2:3], 0x58
	s_ashr_i32 s14, s11, 8
	s_add_i32 s12, s14, s4
	s_ashr_i32 s13, s12, 31
	s_lshl_b64 s[12:13], s[12:13], 21
	s_waitcnt lgkmcnt(0)
	s_add_u32 s2, s2, s12
	s_addc_u32 s3, s3, s13
	s_lshl_b32 s12, s11, 5
	s_and_b32 s12, s12, 0x60
	s_lshl_b32 s13, s14, 7
	v_or_b32_e32 v1, s12, v3
	s_or_b32 s12, s13, s12
	s_ashr_i32 s13, s12, 31
	s_lshl_b64 s[12:13], s[12:13], 13
	s_add_u32 s12, s6, s12
	s_addc_u32 s13, s7, s13
	s_lshl_b32 s14, s11, 4
	s_and_b32 s14, s14, 0xfc0
	v_add_u32_e32 v22, s14, v32
	v_lshlrev_b32_e32 v152, 2, v1
	v_ashrrev_i32_e32 v23, 31, v22
	v_lshl_add_u64 v[24:25], s[2:3], 0, v[152:153]
	v_lshlrev_b64 v[22:23], 9, v[22:23]
	v_lshl_add_u64 v[22:23], v[24:25], 0, v[22:23]
	s_movk_i32 s2, 0x1000
	v_add_co_u32_e32 v24, vcc, s2, v22
	s_movk_i32 s2, 0x3000
	s_nop 0
	v_addc_co_u32_e32 v25, vcc, 0, v23, vcc
	v_add_co_u32_e32 v28, vcc, s30, v22
	s_nop 0
	v_addc_co_u32_e32 v29, vcc, 0, v23, vcc
	v_add_co_u32_e32 v30, vcc, s2, v22
	s_movk_i32 s2, 0x7000
	s_nop 0
	v_addc_co_u32_e32 v31, vcc, 0, v23, vcc
	v_add_co_u32_e32 v34, vcc, s27, v22
	s_nop 1
	v_addc_co_u32_e32 v35, vcc, 0, v23, vcc
	global_load_dword v1, v[22:23], off
	global_load_dword v36, v[22:23], off offset:1024
	global_load_dword v37, v[22:23], off offset:2048
	global_load_dword v38, v[22:23], off offset:3072
	global_load_dword v39, v[24:25], off offset:1024
	global_load_dword v40, v[24:25], off offset:2048
	global_load_dword v41, v[24:25], off offset:3072
	global_load_dword v42, v[30:31], off offset:1024
	global_load_dword v43, v[28:29], off offset:-4096
	global_load_dword v44, v[28:29], off
	global_load_dword v45, v[28:29], off offset:1024
	global_load_dword v46, v[28:29], off offset:2048
	global_load_dword v47, v[28:29], off offset:3072
	global_load_dword v48, v[34:35], off offset:-4096
	global_load_dword v49, v[34:35], off
	v_add_co_u32_e32 v24, vcc, s31, v22
	s_nop 1
	v_addc_co_u32_e32 v25, vcc, 0, v23, vcc
	v_add_co_u32_e32 v28, vcc, s40, v22
	s_nop 1
	v_addc_co_u32_e32 v29, vcc, 0, v23, vcc
	v_add_co_u32_e32 v22, vcc, s2, v22
	global_load_dword v50, v[30:31], off offset:2048
	s_nop 0
	global_load_dword v30, v[30:31], off offset:3072
	s_nop 0
	global_load_dword v31, v[24:25], off offset:1024
	global_load_dword v51, v[24:25], off offset:2048
	s_nop 0
	global_load_dword v24, v[24:25], off offset:3072
	s_nop 0
	global_load_dword v25, v[34:35], off offset:1024
	global_load_dword v52, v[34:35], off offset:2048
	s_nop 0
	global_load_dword v34, v[34:35], off offset:3072
	s_nop 0
	global_load_dword v35, v[28:29], off offset:-4096
	global_load_dword v53, v[28:29], off
	global_load_dword v54, v[28:29], off offset:1024
	global_load_dword v55, v[28:29], off offset:2048
	s_nop 0
	global_load_dword v28, v[28:29], off offset:3072
	v_addc_co_u32_e32 v23, vcc, 0, v23, vcc
	global_load_dword v29, v[22:23], off
	global_load_dword v56, v[22:23], off offset:1024
	global_load_dword v57, v[22:23], off offset:2048
	s_nop 0
	global_load_dword v22, v[22:23], off offset:3072
	v_add_u32_e32 v23, v26, v33
	v_add_u32_e32 v58, 0x400, v23
	v_add_u32_e32 v59, 0x800, v23
	v_add_u32_e32 v60, 0xc00, v23
	v_add_u32_e32 v61, 0x1000, v23
	v_add_u32_e32 v62, 0x1400, v23
	s_lshr_b32 s2, s11, 8
	s_lshl_b32 s2, s2, 20
	s_and_b32 s3, s11, 3
	s_lshl_b32 s3, s3, 18
	s_or_b32 s2, s2, s3
	s_bfe_u32 s3, s11, 0x60002
	s_lshl_b32 s3, s3, 12
	s_or_b32 s2, s2, s3
	s_add_u32 s2, s6, s2
	s_addc_u32 s3, s7, 0
	s_waitcnt vmcnt(30)
	ds_write2_b32 v23, v1, v36 offset1:66
	s_waitcnt vmcnt(28)
	ds_write2_b32 v23, v37, v38 offset0:132 offset1:198
	s_waitcnt vmcnt(23)
	ds_write2_b32 v58, v43, v39 offset0:8 offset1:74
	ds_write2_b32 v58, v40, v41 offset0:140 offset1:206
	s_waitcnt vmcnt(21)
	ds_write2_b32 v59, v44, v45 offset0:16 offset1:82
	s_waitcnt vmcnt(19)
	ds_write2_b32 v59, v46, v47 offset0:148 offset1:214
	s_waitcnt vmcnt(18)
	ds_write2_b32 v60, v48, v42 offset0:24 offset1:90
	s_waitcnt vmcnt(15)
	ds_write2_b32 v60, v50, v30 offset0:156 offset1:222
	s_waitcnt vmcnt(11)
	ds_write2_b32 v61, v49, v25 offset0:32 offset1:98
	s_waitcnt vmcnt(9)
	ds_write2_b32 v61, v52, v34 offset0:164 offset1:230
	s_waitcnt vmcnt(8)
	ds_write2_b32 v62, v35, v31 offset0:40 offset1:106
	ds_write2_b32 v62, v51, v24 offset0:172 offset1:238
	v_add_u32_e32 v1, 0x1800, v23
	s_waitcnt vmcnt(6)
	ds_write2_b32 v1, v53, v54 offset0:48 offset1:114
	s_waitcnt vmcnt(4)
	ds_write2_b32 v1, v55, v28 offset0:180 offset1:246
	v_add_u32_e32 v1, 0x1c00, v23
	s_waitcnt vmcnt(2)
	ds_write2_b32 v1, v29, v56 offset0:56 offset1:122
	s_waitcnt vmcnt(0)
	ds_write2_b32 v1, v57, v22 offset0:188 offset1:254
	s_waitcnt lgkmcnt(0)
	ds_read2_b32 v[28:29], v27 offset1:8
	ds_read2_b32 v[34:35], v27 offset0:33 offset1:41
	ds_read2_b32 v[36:37], v27 offset0:66 offset1:74
	ds_read2_b32 v[38:39], v27 offset0:99 offset1:107
	v_lshlrev_b32_e32 v152, 6, v2
	v_lshrrev_b32_e32 v1, 9, v4
	v_add_u32_e32 v152, v152, v1
	v_lshl_add_u64 v[30:31], s[2:3], 0, v[152:153]
	s_waitcnt lgkmcnt(3)
	v_bfe_u32 v1, v28, 16, 1
	s_movk_i32 s2, 0x7fff
	v_add3_u32 v1, v28, v1, s2
	s_waitcnt lgkmcnt(2)
	v_bfe_u32 v22, v34, 16, 1
	ds_read2_b32 v[40:41], v27 offset0:132 offset1:140
	v_lshrrev_b32_e32 v1, 16, v1
	v_add3_u32 v22, v34, v22, s2
	s_mov_b32 s3, 0xffff0000
	ds_read2_b32 v[42:43], v27 offset0:165 offset1:173
	v_and_or_b32 v22, v22, s3, v1
	s_waitcnt lgkmcnt(3)
	v_bfe_u32 v1, v36, 16, 1
	v_add3_u32 v1, v36, v1, s2
	s_waitcnt lgkmcnt(2)
	v_bfe_u32 v23, v38, 16, 1
	ds_read2_b32 v[44:45], v27 offset0:198 offset1:206
	v_lshrrev_b32_e32 v1, 16, v1
	v_add3_u32 v23, v38, v23, s2
	ds_read2_b32 v[46:47], v27 offset0:231 offset1:239
	v_and_or_b32 v23, v23, s3, v1
	s_waitcnt lgkmcnt(3)
	v_bfe_u32 v1, v40, 16, 1
	v_add3_u32 v1, v40, v1, s2
	s_waitcnt lgkmcnt(2)
	v_bfe_u32 v24, v42, 16, 1
	v_lshrrev_b32_e32 v1, 16, v1
	v_add3_u32 v24, v42, v24, s2
	v_and_or_b32 v24, v24, s3, v1
	s_waitcnt lgkmcnt(1)
	v_bfe_u32 v1, v44, 16, 1
	v_add3_u32 v1, v44, v1, s2
	s_waitcnt lgkmcnt(0)
	v_bfe_u32 v25, v46, 16, 1
	v_lshrrev_b32_e32 v1, 16, v1
	v_add3_u32 v25, v46, v25, s2
	v_and_or_b32 v25, v25, s3, v1
	v_bfe_u32 v1, v29, 16, 1
	global_store_dwordx4 v[30:31], v[22:25], off
	v_add3_u32 v1, v29, v1, s2
	v_lshrrev_b32_e32 v1, 16, v1
	v_bfe_u32 v22, v35, 16, 1
	v_add3_u32 v22, v35, v22, s2
	v_and_or_b32 v22, v22, s3, v1
	v_bfe_u32 v1, v37, 16, 1
	v_add3_u32 v1, v37, v1, s2
	v_bfe_u32 v23, v39, 16, 1
	v_lshrrev_b32_e32 v1, 16, v1
	v_add3_u32 v23, v39, v23, s2
	v_and_or_b32 v23, v23, s3, v1
	v_bfe_u32 v1, v41, 16, 1
	v_add3_u32 v1, v41, v1, s2
	v_bfe_u32 v24, v43, 16, 1
	v_lshrrev_b32_e32 v1, 16, v1
	v_add3_u32 v24, v43, v24, s2
	v_and_or_b32 v24, v24, s3, v1
	v_bfe_u32 v1, v45, 16, 1
	v_add3_u32 v1, v45, v1, s2
	v_bfe_u32 v25, v47, 16, 1
	v_lshrrev_b32_e32 v1, 16, v1
	v_add3_u32 v25, v47, v25, s2
	ds_read2_b32 v[28:29], v27 offset0:16 offset1:24
	v_and_or_b32 v25, v25, s3, v1
	global_store_dwordx4 v[30:31], v[22:25], off offset:128
	ds_read2_b32 v[34:35], v27 offset0:49 offset1:57
	ds_read2_b32 v[36:37], v27 offset0:82 offset1:90
	ds_read2_b32 v[38:39], v27 offset0:115 offset1:123
	s_waitcnt lgkmcnt(3)
	v_bfe_u32 v1, v28, 16, 1
	v_add3_u32 v1, v28, v1, s2
	s_waitcnt lgkmcnt(2)
	v_bfe_u32 v22, v34, 16, 1
	ds_read2_b32 v[40:41], v27 offset0:148 offset1:156
	v_lshrrev_b32_e32 v1, 16, v1
	v_add3_u32 v22, v34, v22, s2
	ds_read2_b32 v[42:43], v27 offset0:181 offset1:189
	v_and_or_b32 v22, v22, s3, v1
	s_waitcnt lgkmcnt(3)
	v_bfe_u32 v1, v36, 16, 1
	v_add3_u32 v1, v36, v1, s2
	s_waitcnt lgkmcnt(2)
	v_bfe_u32 v23, v38, 16, 1
	ds_read2_b32 v[44:45], v27 offset0:214 offset1:222
	v_lshrrev_b32_e32 v1, 16, v1
	v_add3_u32 v23, v38, v23, s2
	ds_read2_b32 v[46:47], v27 offset0:247 offset1:255
	v_and_or_b32 v23, v23, s3, v1
	s_waitcnt lgkmcnt(3)
	v_bfe_u32 v1, v40, 16, 1
	v_add3_u32 v1, v40, v1, s2
	s_waitcnt lgkmcnt(2)
	v_bfe_u32 v24, v42, 16, 1
	v_lshrrev_b32_e32 v1, 16, v1
	v_add3_u32 v24, v42, v24, s2
	v_and_or_b32 v24, v24, s3, v1
	s_waitcnt lgkmcnt(1)
	v_bfe_u32 v1, v44, 16, 1
	v_add3_u32 v1, v44, v1, s2
	s_waitcnt lgkmcnt(0)
	v_bfe_u32 v25, v46, 16, 1
	v_lshrrev_b32_e32 v1, 16, v1
	v_add3_u32 v25, v46, v25, s2
	v_and_or_b32 v25, v25, s3, v1
	v_bfe_u32 v1, v29, 16, 1
	global_store_dwordx4 v[30:31], v[22:25], off offset:256
	v_add3_u32 v1, v29, v1, s2
	v_lshrrev_b32_e32 v1, 16, v1
	v_bfe_u32 v22, v35, 16, 1
	v_add3_u32 v22, v35, v22, s2
	v_and_or_b32 v22, v22, s3, v1
	v_bfe_u32 v1, v37, 16, 1
	v_add3_u32 v1, v37, v1, s2
	v_bfe_u32 v23, v39, 16, 1
	v_lshrrev_b32_e32 v1, 16, v1
	v_add3_u32 v23, v39, v23, s2
	v_and_or_b32 v23, v23, s3, v1
	v_bfe_u32 v1, v41, 16, 1
	v_add3_u32 v1, v41, v1, s2
	v_bfe_u32 v24, v43, 16, 1
	v_lshrrev_b32_e32 v1, 16, v1
	v_add3_u32 v24, v43, v24, s2
	v_and_or_b32 v24, v24, s3, v1
	v_bfe_u32 v1, v45, 16, 1
	v_add3_u32 v1, v45, v1, s2
	v_bfe_u32 v25, v47, 16, 1
	v_lshrrev_b32_e32 v1, 16, v1
	v_add3_u32 v25, v47, v25, s2
	v_and_or_b32 v25, v25, s3, v1
	global_store_dwordx4 v[30:31], v[22:25], off offset:384
	s_waitcnt lgkmcnt(0)
	s_branch .LBB0_115

.LBB0_332:
	s_lshl_b32 s0, s6, 4
	s_and_b32 s5, s0, 0x600
	s_lshl_b32 s0, s7, 6
	s_ashr_i32 s10, s7, 3
	s_and_b32 s11, s0, 0x100
	s_lshr_b32 s0, s10, 28
	s_add_i32 s1, s10, s0
	s_ashr_i32 s0, s1, 4
	s_and_b32 s1, s1, -16
	s_sub_i32 s8, s10, s1
	s_mov_b64 s[12:13], s[54:55]
	s_lshl_b32 s14, s0, 8
	s_mov_b64 s[16:17], s[54:55]
	s_ashr_i32 s1, s0, 31
	s_lshr_b32 s9, s7, 2
	v_mbcnt_lo_u32_b32 v64, -1, 0
	v_mbcnt_hi_u32_b32 v64, -1, v64
	s_ashr_i32 s15, s14, 31
	s_lshl_b64 s[18:19], s[0:1], 20
	v_readlane_b32 s20, v254, 6
	v_readlane_b32 s21, v254, 7
	s_lshl_b64 s[20:21], s[20:21], 5
	s_add_u32 s16, s16, s20
	s_addc_u32 s17, s17, s21
	v_and_b32_e32 v92, 31, v64
	s_add_u32 s16, s16, s18
	v_lshlrev_b32_e32 v152, 4, v64
	s_addc_u32 s17, s17, s19
	v_lshl_add_u64 v[68:69], s[16:17], 0, v[152:153]
	v_readlane_b32 s16, v254, 8
	s_add_u32 s16, s12, s16
	v_readlane_b32 s12, v254, 9
	s_addc_u32 s17, s13, s12
	s_lshl_b64 s[12:13], s[14:15], 1
	v_lshl_or_b32 v2, v92, 4, s5
	s_add_u32 s5, s16, s12
	s_addc_u32 s12, s17, s13
	s_add_u32 s5, s5, s11
	v_ashrrev_i32_e32 v93, 5, v64
	s_mul_i32 s19, s8, 0x1c00000
	s_addc_u32 s11, s12, 0
	v_lshlrev_b32_e32 v0, 3, v93
	s_mul_hi_i32 s18, s8, 0x1c00000
	s_add_u32 s12, s5, s19
	v_ashrrev_i32_e32 v1, 31, v0
	s_addc_u32 s13, s11, s18
	v_lshlrev_b64 v[66:67], 1, v[0:1]
	v_mov_b64_e32 v[0:1], s[12:13]
	s_movk_i32 s5, 0x3800
	v_mov_b32_e32 v48, 0
	s_mov_b32 s4, 4
	v_mad_u64_u32 v[70:71], s[12:13], v2, s5, v[0:1]
	v_mov_b32_e32 v49, v48
	v_mov_b32_e32 v50, v48
	v_mov_b32_e32 v51, v48
	v_mov_b32_e32 v52, v48
	v_mov_b32_e32 v53, v48
	v_mov_b32_e32 v54, v48
	v_mov_b32_e32 v55, v48
	v_mov_b32_e32 v56, v48
	v_mov_b32_e32 v57, v48
	v_mov_b32_e32 v58, v48
	v_mov_b32_e32 v59, v48
	v_mov_b32_e32 v60, v48
	v_mov_b32_e32 v61, v48
	v_mov_b32_e32 v62, v48
	v_mov_b32_e32 v63, v48
	v_mov_b32_e32 v32, v48
	v_mov_b32_e32 v33, v48
	v_mov_b32_e32 v34, v48
	v_mov_b32_e32 v35, v48
	v_mov_b32_e32 v36, v48
	v_mov_b32_e32 v37, v48
	v_mov_b32_e32 v38, v48
	v_mov_b32_e32 v39, v48
	v_mov_b32_e32 v40, v48
	v_mov_b32_e32 v41, v48
	v_mov_b32_e32 v42, v48
	v_mov_b32_e32 v43, v48
	v_mov_b32_e32 v44, v48
	v_mov_b32_e32 v45, v48
	v_mov_b32_e32 v46, v48
	v_mov_b32_e32 v47, v48
	v_mov_b32_e32 v16, v48
	v_mov_b32_e32 v17, v48
	v_mov_b32_e32 v18, v48
	v_mov_b32_e32 v19, v48
	v_mov_b32_e32 v20, v48
	v_mov_b32_e32 v21, v48
	v_mov_b32_e32 v22, v48
	v_mov_b32_e32 v23, v48
	v_mov_b32_e32 v24, v48
	v_mov_b32_e32 v25, v48
	v_mov_b32_e32 v26, v48
	v_mov_b32_e32 v27, v48
	v_mov_b32_e32 v28, v48
	v_mov_b32_e32 v29, v48
	v_mov_b32_e32 v30, v48
	v_mov_b32_e32 v31, v48
	v_mov_b32_e32 v0, v48
	v_mov_b32_e32 v1, v48
	v_mov_b32_e32 v2, v48
	v_mov_b32_e32 v3, v48
	v_mov_b32_e32 v4, v48
	v_mov_b32_e32 v5, v48
	v_mov_b32_e32 v6, v48
	v_mov_b32_e32 v7, v48
	v_mov_b32_e32 v8, v48
	v_mov_b32_e32 v9, v48
	v_mov_b32_e32 v10, v48
	v_mov_b32_e32 v11, v48
	v_mov_b32_e32 v12, v48
	v_mov_b32_e32 v13, v48
	v_mov_b32_e32 v14, v48
	v_mov_b32_e32 v15, v48
	s_mov_b64 s[14:15], 0x2000
.LBB0_333:
	v_mov_b32_e32 v106, v68
	v_mov_b32_e32 v107, v69
	s_mov_b32 s5, 0x3de00000
	v_add_co_u32_e32 v126, vcc, s5, v106
	s_nop 1
	v_addc_co_u32_e32 v127, vcc, 0, v107, vcc
	s_mov_b32 s5, 0x3de40000
	v_add_co_u32_e32 v128, vcc, s5, v106
	s_nop 1
	v_addc_co_u32_e32 v129, vcc, 0, v107, vcc
	s_mov_b32 s5, 0x3de80000
	v_add_co_u32_e32 v130, vcc, s5, v106
	s_nop 1
	v_addc_co_u32_e32 v131, vcc, 0, v107, vcc
	s_mov_b32 s5, 0x3dec0000
	v_add_co_u32_e32 v132, vcc, s5, v106
	s_nop 1
	v_addc_co_u32_e32 v133, vcc, 0, v107, vcc
	v_add_co_u32_e32 v134, vcc, 0x1000, v126
	s_nop 1
	v_addc_co_u32_e32 v135, vcc, 0, v127, vcc
	v_add_co_u32_e32 v136, vcc, 0x1000, v128
	s_nop 1
	v_addc_co_u32_e32 v137, vcc, 0, v129, vcc
	v_add_co_u32_e32 v138, vcc, 0x1000, v130
	s_nop 1
	v_addc_co_u32_e32 v139, vcc, 0, v131, vcc
	v_add_co_u32_e32 v140, vcc, 0x1000, v132
	s_nop 1
	v_addc_co_u32_e32 v141, vcc, 0, v133, vcc
	v_lshl_add_u64 v[102:103], v[70:71], 0, v[66:67]
	global_load_dwordx4 v[72:75], v[102:103], off offset:-128
	global_load_dwordx4 v[76:79], v[102:103], off offset:-96
	global_load_dwordx4 v[80:83], v[102:103], off offset:-64
	global_load_dwordx4 v[84:87], v[102:103], off offset:-32
	global_load_dwordx4 v[88:91], v[102:103], off
	global_load_dwordx4 v[94:97], v[102:103], off offset:32
	global_load_dwordx4 v[98:101], v[102:103], off offset:64
	s_nop 0
	global_load_dwordx4 v[102:105], v[102:103], off offset:96
	global_load_dwordx4 v[162:165], v[126:127], off
	global_load_dwordx4 v[166:169], v[128:129], off
	global_load_dwordx4 v[170:173], v[130:131], off
	global_load_dwordx4 v[174:177], v[132:133], off
	global_load_dwordx4 v[178:181], v[126:127], off offset:1024
	global_load_dwordx4 v[182:185], v[128:129], off offset:1024
	global_load_dwordx4 v[186:189], v[130:131], off offset:1024
	global_load_dwordx4 v[190:193], v[132:133], off offset:1024
	global_load_dwordx4 v[194:197], v[126:127], off offset:2048
	global_load_dwordx4 v[198:201], v[128:129], off offset:2048
	global_load_dwordx4 v[202:205], v[130:131], off offset:2048
	global_load_dwordx4 v[214:217], v[132:133], off offset:2048
	global_load_dwordx4 v[218:221], v[126:127], off offset:3072
	global_load_dwordx4 v[222:225], v[128:129], off offset:3072
	global_load_dwordx4 v[226:229], v[130:131], off offset:3072
	global_load_dwordx4 v[230:233], v[132:133], off offset:3072
	s_add_i32 s4, s4, -1
	s_mov_b64 s[12:13], 0x3800
	v_lshl_add_u64 v[68:69], v[68:69], 0, s[14:15]
	v_lshl_add_u64 v[70:71], v[70:71], 0, s[12:13]
	s_waitcnt vmcnt(15)
	v_mfma_f32_32x32x16_bf16 v[48:63], v[162:165], v[72:75], v[48:63]
	global_load_dwordx4 v[162:165], v[134:135], off
	s_waitcnt vmcnt(15)
	v_mfma_f32_32x32x16_bf16 v[32:47], v[166:169], v[72:75], v[32:47]
	global_load_dwordx4 v[166:169], v[136:137], off
	s_waitcnt vmcnt(15)
	v_mfma_f32_32x32x16_bf16 v[16:31], v[170:173], v[72:75], v[16:31]
	global_load_dwordx4 v[170:173], v[138:139], off
	s_waitcnt vmcnt(15)
	v_mfma_f32_32x32x16_bf16 v[0:15], v[174:177], v[72:75], v[0:15]
	global_load_dwordx4 v[174:177], v[140:141], off
	s_waitcnt vmcnt(15)
	v_mfma_f32_32x32x16_bf16 v[48:63], v[178:181], v[76:79], v[48:63]
	global_load_dwordx4 v[178:181], v[134:135], off offset:1024
	s_waitcnt vmcnt(15)
	v_mfma_f32_32x32x16_bf16 v[32:47], v[182:185], v[76:79], v[32:47]
	global_load_dwordx4 v[182:185], v[136:137], off offset:1024
	s_waitcnt vmcnt(15)
	v_mfma_f32_32x32x16_bf16 v[16:31], v[186:189], v[76:79], v[16:31]
	global_load_dwordx4 v[186:189], v[138:139], off offset:1024
	s_waitcnt vmcnt(15)
	v_mfma_f32_32x32x16_bf16 v[0:15], v[190:193], v[76:79], v[0:15]
	global_load_dwordx4 v[190:193], v[140:141], off offset:1024
	s_waitcnt vmcnt(15)
	v_mfma_f32_32x32x16_bf16 v[48:63], v[194:197], v[80:83], v[48:63]
	global_load_dwordx4 v[194:197], v[134:135], off offset:2048
	s_waitcnt vmcnt(15)
	v_mfma_f32_32x32x16_bf16 v[32:47], v[198:201], v[80:83], v[32:47]
	global_load_dwordx4 v[198:201], v[136:137], off offset:2048
	s_waitcnt vmcnt(15)
	v_mfma_f32_32x32x16_bf16 v[16:31], v[202:205], v[80:83], v[16:31]
	global_load_dwordx4 v[202:205], v[138:139], off offset:2048
	s_waitcnt vmcnt(15)
	v_mfma_f32_32x32x16_bf16 v[0:15], v[214:217], v[80:83], v[0:15]
	global_load_dwordx4 v[214:217], v[140:141], off offset:2048
	s_waitcnt vmcnt(15)
	v_mfma_f32_32x32x16_bf16 v[48:63], v[218:221], v[84:87], v[48:63]
	global_load_dwordx4 v[218:221], v[134:135], off offset:3072
	s_waitcnt vmcnt(15)
	v_mfma_f32_32x32x16_bf16 v[32:47], v[222:225], v[84:87], v[32:47]
	global_load_dwordx4 v[222:225], v[136:137], off offset:3072
	s_waitcnt vmcnt(15)
	v_mfma_f32_32x32x16_bf16 v[16:31], v[226:229], v[84:87], v[16:31]
	global_load_dwordx4 v[226:229], v[138:139], off offset:3072
	s_waitcnt vmcnt(15)
	v_mfma_f32_32x32x16_bf16 v[0:15], v[230:233], v[84:87], v[0:15]
	global_load_dwordx4 v[230:233], v[140:141], off offset:3072
	s_waitcnt vmcnt(15)
	v_mfma_f32_32x32x16_bf16 v[48:63], v[162:165], v[88:91], v[48:63]
	s_waitcnt vmcnt(14)
	v_mfma_f32_32x32x16_bf16 v[32:47], v[166:169], v[88:91], v[32:47]
	s_waitcnt vmcnt(13)
	v_mfma_f32_32x32x16_bf16 v[16:31], v[170:173], v[88:91], v[16:31]
	s_waitcnt vmcnt(12)
	v_mfma_f32_32x32x16_bf16 v[0:15], v[174:177], v[88:91], v[0:15]
	s_waitcnt vmcnt(11)
	v_mfma_f32_32x32x16_bf16 v[48:63], v[178:181], v[94:97], v[48:63]
	s_waitcnt vmcnt(10)
	v_mfma_f32_32x32x16_bf16 v[32:47], v[182:185], v[94:97], v[32:47]
	s_waitcnt vmcnt(9)
	v_mfma_f32_32x32x16_bf16 v[16:31], v[186:189], v[94:97], v[16:31]
	s_waitcnt vmcnt(8)
	v_mfma_f32_32x32x16_bf16 v[0:15], v[190:193], v[94:97], v[0:15]
	s_waitcnt vmcnt(7)
	v_mfma_f32_32x32x16_bf16 v[48:63], v[194:197], v[98:101], v[48:63]
	s_waitcnt vmcnt(6)
	v_mfma_f32_32x32x16_bf16 v[32:47], v[198:201], v[98:101], v[32:47]
	s_waitcnt vmcnt(5)
	v_mfma_f32_32x32x16_bf16 v[16:31], v[202:205], v[98:101], v[16:31]
	s_waitcnt vmcnt(4)
	v_mfma_f32_32x32x16_bf16 v[0:15], v[214:217], v[98:101], v[0:15]
	s_waitcnt vmcnt(3)
	v_mfma_f32_32x32x16_bf16 v[48:63], v[218:221], v[102:105], v[48:63]
	s_waitcnt vmcnt(2)
	v_mfma_f32_32x32x16_bf16 v[32:47], v[222:225], v[102:105], v[32:47]
	s_waitcnt vmcnt(1)
	v_mfma_f32_32x32x16_bf16 v[16:31], v[226:229], v[102:105], v[16:31]
	s_waitcnt vmcnt(0)
	v_mfma_f32_32x32x16_bf16 v[0:15], v[230:233], v[102:105], v[0:15]
	s_cmp_eq_u32 s4, 0
	s_cbranch_scc0 .LBB0_333
	v_lshl_add_u32 v65, v64, 2, s72
	s_nop 4
	ds_write2st64_b32 v65, v48, v49 offset1:1
	ds_write2st64_b32 v65, v50, v51 offset0:2 offset1:3
	ds_write2st64_b32 v65, v52, v53 offset0:4 offset1:5
	ds_write2st64_b32 v65, v54, v55 offset0:6 offset1:7
	ds_write2st64_b32 v65, v56, v57 offset0:8 offset1:9
	ds_write2st64_b32 v65, v58, v59 offset0:10 offset1:11
	ds_write2st64_b32 v65, v60, v61 offset0:12 offset1:13
	ds_write2st64_b32 v65, v62, v63 offset0:14 offset1:15
	ds_write2st64_b32 v65, v32, v33 offset0:16 offset1:17
	ds_write2st64_b32 v65, v34, v35 offset0:18 offset1:19
	ds_write2st64_b32 v65, v36, v37 offset0:20 offset1:21
	ds_write2st64_b32 v65, v38, v39 offset0:22 offset1:23
	ds_write2st64_b32 v65, v40, v41 offset0:24 offset1:25
	ds_write2st64_b32 v65, v42, v43 offset0:26 offset1:27
	ds_write2st64_b32 v65, v44, v45 offset0:28 offset1:29
	ds_write2st64_b32 v65, v46, v47 offset0:30 offset1:31
	ds_write2st64_b32 v65, v16, v17 offset0:32 offset1:33
	ds_write2st64_b32 v65, v18, v19 offset0:34 offset1:35
	ds_write2st64_b32 v65, v20, v21 offset0:36 offset1:37
	ds_write2st64_b32 v65, v22, v23 offset0:38 offset1:39
	ds_write2st64_b32 v65, v24, v25 offset0:40 offset1:41
	ds_write2st64_b32 v65, v26, v27 offset0:42 offset1:43
	ds_write2st64_b32 v65, v28, v29 offset0:44 offset1:45
	ds_write2st64_b32 v65, v30, v31 offset0:46 offset1:47
	ds_write2st64_b32 v65, v0, v1 offset0:48 offset1:49
	ds_write2st64_b32 v65, v2, v3 offset0:50 offset1:51
	ds_write2st64_b32 v65, v4, v5 offset0:52 offset1:53
	ds_write2st64_b32 v65, v6, v7 offset0:54 offset1:55
	ds_write2st64_b32 v65, v8, v9 offset0:56 offset1:57
	ds_write2st64_b32 v65, v10, v11 offset0:58 offset1:59
	ds_write2st64_b32 v65, v12, v13 offset0:60 offset1:61
	ds_write2st64_b32 v65, v14, v15 offset0:62 offset1:63
	s_waitcnt lgkmcnt(0)
	v_readlane_b32 s4, v252, 30
	v_readlane_b32 s5, v252, 31
	s_and_b64 vcc, exec, s[4:5]
	s_waitcnt lgkmcnt(0)
	s_barrier
	s_cbranch_vccz .LBB0_336
	s_barrier
	s_cbranch_execnz .LBB0_331
	s_branch .LBB0_337
